# attention first half-step, unmasked tiles: partialSM serial chain (row max, lane exchange, running max, rescale factor test) issued in the PV MFMA gaps of a second PV copy, temporaries renamed out of
# baseline (speedup 1.0000x reference)
; __device__ __forceinline__ void finishSM(f32x16& p0, f32x16& p1, float alpha, float& l_reg, bf16x8& pa0, bf16x8& pa1, bf16x8& pa2, bf16x8& pa3) {
;     for (int r = 0; r < 16; ++r) p1[r] = __builtin_amdgcn_exp2f(p1[r]);
;     float ps = 0; for (int r = 0; r < 16; ++r) ps += p0[r]; for (int r = 0; r < 16; ++r) ps += p1[r];
;     { auto rr = __builtin_amdgcn_permlane32_swap(__float_as_uint(ps), __float_as_uint(ps), false, false);
;       ps = __uint_as_float(rr[0]) + __uint_as_float(rr[1]); }
;     l_reg = l_reg * alpha + ps;
;     ...
;     PK4(p0, 0, pa0); PK4(p0, 8, pa1); PK4(p1, 0, pa2); PK4(p1, 8, pa3);
;     ...
; }
; template <int KB>
; __device__ __forceinline__ void qkt(f32x16& p0, f32x16& p1, const char* K_lds, int r32, int hi, const bf16x8* qr) {
;     p0 = f32x16{}; p1 = f32x16{};
;     const char* kb[4];
; #pragma unroll
;     for (int dd = 0; dd < 4; ++dd) kb[dd] = K_lds + KB * SHM_K + KSWZ(r32, (dd * 16 + hi * 8) * 2);
; #pragma unroll
;     for (int d0 = 0; d0 < 8; ++d0) { const char* a = kb[d0 & 3] + (d0 >> 2) * 128;
;         bf16x8 b0 = *reinterpret_cast<const bf16x8*>(a);
;         bf16x8 b1 = *reinterpret_cast<const bf16x8*>(a + 32 * 256);
;         p0 = __builtin_amdgcn_mfma_f32_32x32x16_bf16(b0, qr[d0], p0, 0, 0, 0);
;         p1 = __builtin_amdgcn_mfma_f32_32x32x16_bf16(b1, qr[d0], p1, 0, 0, 0); }
; }
.LBB0_89:
	ds_read_b128 v[66:69], v169 offset:49152
	ds_read_b128 v[70:73], v169 offset:57344
	ds_read_b128 v[100:103], v193 offset:49152
	ds_read_b128 v[136:139], v193 offset:57344
	ds_read_b128 v[234:237], v194 offset:49152
	ds_read_b128 v[238:241], v194 offset:57344
	v_add_f32_e32 v148, 0, v231
	v_add_f32_e32 v148, v233, v148
	v_add_f32_e32 v148, v229, v148
	v_add_f32_e32 v148, v232, v148
	v_add_f32_e32 v148, v228, v148
	v_add_f32_e32 v148, v230, v148
	v_add_f32_e32 v148, v226, v148
	v_add_f32_e32 v148, v227, v148
	v_add_f32_e32 v148, v223, v148
	v_add_f32_e32 v148, v225, v148
	v_add_f32_e32 v148, v209, v148
	v_add_f32_e32 v148, v224, v148
	v_add_f32_e32 v148, v206, v148
	v_add_f32_e32 v148, v208, v148
	v_add_f32_e32 v148, v205, v148
	v_add_f32_e32 v148, v207, v148
	v_exp_f32_e32 v140, v152
	v_exp_f32_e32 v141, v153
	v_exp_f32_e32 v142, v180
	v_exp_f32_e32 v143, v181
	s_waitcnt lgkmcnt(5)
	v_mfma_f32_32x32x16_bf16 v[82:97], v[66:69], v[132:135], 0
	v_exp_f32_e32 v144, v160
	v_exp_f32_e32 v145, v161
	v_exp_f32_e32 v146, v154
	v_exp_f32_e32 v147, v155
	s_waitcnt lgkmcnt(4)
	v_mfma_f32_32x32x16_bf16 v[66:81], v[70:73], v[132:135], 0
	v_exp_f32_e32 v178, v178
	v_exp_f32_e32 v179, v179
	v_exp_f32_e32 v162, v162
	v_exp_f32_e32 v163, v163
	s_waitcnt lgkmcnt(3)
	v_mfma_f32_32x32x16_bf16 v[82:97], v[100:103], v[128:131], v[82:97]
	v_add_f32_e32 v148, v178, v148
	v_add_f32_e32 v148, v179, v148
	v_add_f32_e32 v148, v162, v148
	v_exp_f32_e32 v158, v158
	s_waitcnt lgkmcnt(2)
	v_mfma_f32_32x32x16_bf16 v[66:81], v[136:139], v[128:131], v[66:81]
	v_exp_f32_e32 v159, v159
	v_exp_f32_e32 v156, v156
	v_exp_f32_e32 v157, v157
	v_add_f32_e32 v148, v163, v148
	ds_read_b128 v[100:103], v195 offset:49152
	ds_read_b128 v[136:139], v195 offset:57344
	s_waitcnt lgkmcnt(3)
	v_mfma_f32_32x32x16_bf16 v[82:97], v[234:237], v[124:127], v[82:97]
	v_add_f32_e32 v148, v158, v148
	v_add_f32_e32 v148, v159, v148
	v_add_f32_e32 v148, v156, v148
	v_add_f32_e32 v148, v157, v148
	s_waitcnt lgkmcnt(2)
	v_mfma_f32_32x32x16_bf16 v[66:81], v[238:241], v[124:127], v[66:81]
	v_add_f32_e32 v148, v140, v148
	v_add_f32_e32 v148, v141, v148
	v_add_f32_e32 v148, v142, v148
	v_add_f32_e32 v148, v143, v148
	ds_read_b128 v[234:237], v169 offset:49280
	ds_read_b128 v[238:241], v169 offset:57472
	s_waitcnt lgkmcnt(3)
	v_mfma_f32_32x32x16_bf16 v[82:97], v[100:103], v[120:123], v[82:97]
	v_add_f32_e32 v148, v144, v148
	v_add_f32_e32 v148, v145, v148
	v_add_f32_e32 v148, v146, v148
	v_add_f32_e32 v199, v147, v148
	s_waitcnt lgkmcnt(2)
	v_mfma_f32_32x32x16_bf16 v[66:81], v[136:139], v[120:123], v[66:81]
	v_mov_b32_e32 v200, v199
	s_nop 1
	v_permlane32_swap_b32_e32 v199, v200
	v_cvt_pk_bf16_f32 v148, v231, v233
	v_cvt_pk_bf16_f32 v149, v229, v232
	v_cvt_pk_bf16_f32 v150, v228, v230
	ds_read_b128 v[100:103], v193 offset:49280
	ds_read_b128 v[136:139], v193 offset:57472
	s_waitcnt lgkmcnt(3)
	v_mfma_f32_32x32x16_bf16 v[82:97], v[234:237], v[116:119], v[82:97]
	v_cvt_pk_bf16_f32 v151, v226, v227
	v_cvt_pk_bf16_f32 v152, v223, v225
	v_cvt_pk_bf16_f32 v153, v209, v224
	s_waitcnt lgkmcnt(2)
	v_mfma_f32_32x32x16_bf16 v[66:81], v[238:241], v[116:119], v[66:81]
	v_cvt_pk_bf16_f32 v154, v206, v208
	v_cvt_pk_bf16_f32 v155, v205, v207
	v_cvt_pk_bf16_f32 v158, v158, v159
	ds_read_b128 v[234:237], v194 offset:49280
	ds_read_b128 v[238:241], v194 offset:57472
	s_waitcnt lgkmcnt(3)
	v_mfma_f32_32x32x16_bf16 v[82:97], v[100:103], v[112:115], v[82:97]
	v_cvt_pk_bf16_f32 v159, v156, v157
	v_cvt_pk_bf16_f32 v156, v178, v179
	v_cvt_pk_bf16_f32 v157, v162, v163
	s_waitcnt lgkmcnt(2)
	v_mfma_f32_32x32x16_bf16 v[66:81], v[136:139], v[112:115], v[66:81]
	v_cvt_pk_bf16_f32 v160, v140, v141
	v_cvt_pk_bf16_f32 v161, v142, v143
	v_cvt_pk_bf16_f32 v162, v144, v145
	ds_read_b128 v[100:103], v195 offset:49280
	ds_read_b128 v[136:139], v195 offset:57472
	ds_read_b64_tr_b16 v[172:173], v185 offset:0
	ds_read_b64_tr_b16 v[174:175], v185 offset:0x800
	ds_read_b64_tr_b16 v[202:203], v185 offset:0x1000
	ds_read_b64_tr_b16 v[204:205], v185 offset:0x1800
	ds_read_b64_tr_b16 v[206:207], v185 offset:0x2000
	ds_read_b64_tr_b16 v[208:209], v185 offset:0x2800
	ds_read_b64_tr_b16 v[224:225], v185 offset:0x3000
	ds_read_b64_tr_b16 v[226:227], v185 offset:0x3800
	s_waitcnt lgkmcnt(11)
	v_mfma_f32_32x32x16_bf16 v[82:97], v[234:237], v[108:111], v[82:97]
	v_cvt_pk_bf16_f32 v163, v146, v147
	s_nop 0
	v_permlane32_swap_b32_e32 v148, v150
	v_permlane32_swap_b32_e32 v149, v151
	s_waitcnt lgkmcnt(10)
	v_mfma_f32_32x32x16_bf16 v[66:81], v[238:241], v[108:111], v[66:81]
	v_permlane32_swap_b32_e32 v152, v154
	v_permlane32_swap_b32_e32 v153, v155
	v_permlane32_swap_b32_e32 v156, v158
	s_waitcnt lgkmcnt(9)
	v_mfma_f32_32x32x16_bf16 v[82:97], v[100:103], v[104:107], v[82:97]
	v_permlane32_swap_b32_e32 v157, v159
	v_permlane32_swap_b32_e32 v160, v162
	v_permlane32_swap_b32_e32 v161, v163
	s_waitcnt lgkmcnt(8)
	v_mfma_f32_32x32x16_bf16 v[66:81], v[136:139], v[104:107], v[66:81]
	v_add_u32_e32 v169, s100, v169
	v_add_u32_e32 v193, s100, v193
	v_add_u32_e32 v194, s100, v194
	v_add_u32_e32 v195, s100, v195
	s_sub_i32 s100, 0, s100
	s_sub_i32 m0, 0, s100
	s_max_i32 m0, m0, 0
	s_add_i32 m0, m0, s32
	s_add_i32 m0, m0, 0x4000
	s_nop 0
	global_load_lds_dwordx4 v[244:245], off
	s_add_i32 m0, m0, 0x2000
	s_nop 0
	global_load_lds_dwordx4 v[246:247], off
	v_lshl_add_u64 v[244:245], v[244:245], 0, v[250:251]
	v_lshl_add_u64 v[246:247], v[246:247], 0, v[250:251]
	s_sub_i32 m0, 0, s100
	s_max_i32 m0, m0, 0
	s_add_i32 m0, m0, s32
	s_add_i32 m0, m0, s32
	s_sub_i32 m0, m0, 0x10000
	s_nop 0
	global_load_lds_dwordx4 v[248:249], off
	s_add_i32 m0, m0, 896
	s_nop 0
	global_load_lds_dwordx4 v[248:249], off offset:128
	v_lshl_add_u64 v[248:249], v[248:249], 0, v[250:251]
	s_nop 0
	s_cmp_le_i32 s7, s6
	s_cbranch_scc0 .Lmy_pv1_slow
; __device__ __forceinline__ void partialSM(f32x16& p0, f32x16& p1, float& m_reg, float& mn, float& alpha, bool rs) {
;     float pmax = p0[0]; for (int r = 1; r < 16; ++r) pmax = fmaxf(pmax, p0[r]); for (int r = 0; r < 16; ++r) pmax = fmaxf(pmax, p1[r]);
;     if (!rs) pmax = -__builtin_inff();
;     { auto rr = __builtin_amdgcn_permlane32_swap(__float_as_uint(pmax), __float_as_uint(pmax), false, false);
;       pmax = fmaxf(__uint_as_float(rr[0]), __uint_as_float(rr[1])); }
;     constexpr float C2 = 1.4426950408889634f * SCALE;
;     if (__builtin_expect(__all((pmax - m_reg) * SCALE <= THR), 1)) { mn = m_reg; alpha = 1.f; }
;     else { mn = fmaxf(m_reg, pmax); alpha = __builtin_amdgcn_exp2f((m_reg - mn) * C2); m_reg = mn; }
; template <int VB>
; __device__ __forceinline__ void pv_tile(f32x16* o, int vb0, bf16x8 pa0, bf16x8 pa1, bf16x8 pa2, bf16x8 pa3) {
;     ...
;     PV_D0(0); PV_D0(1); PV_D0(2); PV_D0(3);
	s_waitcnt lgkmcnt(6)
	v_mfma_f32_32x32x16_bf16 v[50:65], v[148:151], v[172:175], v[50:65]
	ds_read_b64_tr_b16 v[172:173], v185 offset:0x200
	ds_read_b64_tr_b16 v[174:175], v185 offset:0xa00
	s_add_i32 s0, s3, -2
	s_lshr_b32 s8, s0, 2
	s_cmp_ge_i32 s8, s44
	s_waitcnt lgkmcnt(6)
	v_mfma_f32_32x32x16_bf16 v[50:65], v[152:155], v[202:205], v[50:65]
	ds_read_b64_tr_b16 v[202:203], v185 offset:0x1200
	ds_read_b64_tr_b16 v[204:205], v185 offset:0x1a00
	s_cselect_b64 s[0:1], -1, 0
	s_lshl_b32 s8, 1, s8
	v_and_b32_e32 v217, s8, v165
	s_waitcnt lgkmcnt(6)
	v_mfma_f32_32x32x16_bf16 v[50:65], v[156:159], v[206:209], v[50:65]
	ds_read_b64_tr_b16 v[206:207], v185 offset:0x2200
	ds_read_b64_tr_b16 v[208:209], v185 offset:0x2a00
	v_cmp_ne_u32_e32 vcc, 0, v217
	v_max_f32_e32 v217, v83, v83
	v_max_f32_e32 v218, v82, v82
	s_waitcnt lgkmcnt(6)
	v_mfma_f32_32x32x16_bf16 v[50:65], v[160:163], v[224:227], v[50:65]
	ds_read_b64_tr_b16 v[224:225], v185 offset:0x3200
	ds_read_b64_tr_b16 v[226:227], v185 offset:0x3a00
	v_max_f32_e32 v217, v218, v217
	v_max3_f32 v217, v217, v84, v85
	v_max3_f32 v217, v217, v86, v87
	s_waitcnt lgkmcnt(6)
	v_mfma_f32_32x32x16_bf16 v[34:49], v[148:151], v[172:175], v[34:49]
	ds_read_b64_tr_b16 v[172:173], v185 offset:0x400
	ds_read_b64_tr_b16 v[174:175], v185 offset:0xc00
	v_max3_f32 v217, v217, v88, v89
	v_max3_f32 v217, v217, v90, v91
	v_max3_f32 v217, v217, v92, v93
	s_waitcnt lgkmcnt(6)
	v_mfma_f32_32x32x16_bf16 v[34:49], v[152:155], v[202:205], v[34:49]
	ds_read_b64_tr_b16 v[202:203], v185 offset:0x1400
	ds_read_b64_tr_b16 v[204:205], v185 offset:0x1c00
	v_max3_f32 v217, v217, v94, v95
	v_max3_f32 v217, v217, v96, v97
	v_max3_f32 v217, v217, v66, v67
	s_waitcnt lgkmcnt(6)
	v_mfma_f32_32x32x16_bf16 v[34:49], v[156:159], v[206:209], v[34:49]
	ds_read_b64_tr_b16 v[206:207], v185 offset:0x2400
	ds_read_b64_tr_b16 v[208:209], v185 offset:0x2c00
	v_max3_f32 v217, v217, v68, v69
	v_max3_f32 v217, v217, v70, v71
	v_max3_f32 v217, v217, v72, v73
	s_waitcnt lgkmcnt(6)
	v_mfma_f32_32x32x16_bf16 v[34:49], v[160:163], v[224:227], v[34:49]
	ds_read_b64_tr_b16 v[224:225], v185 offset:0x3400
	ds_read_b64_tr_b16 v[226:227], v185 offset:0x3c00
	v_max3_f32 v217, v217, v74, v75
	v_max3_f32 v217, v217, v76, v77
	v_max3_f32 v217, v217, v78, v79
	s_waitcnt lgkmcnt(6)
	v_mfma_f32_32x32x16_bf16 v[18:33], v[148:151], v[172:175], v[18:33]
	ds_read_b64_tr_b16 v[172:173], v185 offset:0x600
	ds_read_b64_tr_b16 v[174:175], v185 offset:0xe00
	s_or_b64 s[40:41], s[0:1], vcc
	v_max3_f32 v217, v217, v80, v81
	v_cndmask_b32_e64 v217, v220, v217, s[40:41]
	s_waitcnt lgkmcnt(6)
	v_mfma_f32_32x32x16_bf16 v[18:33], v[152:155], v[202:205], v[18:33]
	ds_read_b64_tr_b16 v[202:203], v185 offset:0x1600
	ds_read_b64_tr_b16 v[204:205], v185 offset:0x1e00
	v_mov_b32_e32 v218, v217
	s_nop 1
	v_permlane32_swap_b32_e32 v217, v218
	v_max_f32_e32 v218, v218, v218
	v_max_f32_e32 v217, v217, v217
	s_waitcnt lgkmcnt(6)
	v_mfma_f32_32x32x16_bf16 v[18:33], v[156:159], v[206:209], v[18:33]
	ds_read_b64_tr_b16 v[206:207], v185 offset:0x2600
	ds_read_b64_tr_b16 v[208:209], v185 offset:0x2e00
	v_max_f32_e32 v217, v217, v218
	v_sub_f32_e32 v218, v217, v198
	v_mul_f32_e32 v218, 0x3db504f3, v218
	s_waitcnt lgkmcnt(6)
	v_mfma_f32_32x32x16_bf16 v[18:33], v[160:163], v[224:227], v[18:33]
	ds_read_b64_tr_b16 v[224:225], v185 offset:0x3600
	ds_read_b64_tr_b16 v[226:227], v185 offset:0x3e00
	v_cmp_ge_f32_e32 vcc, s91, v218
	v_max_f32_e32 v218, v198, v198
	v_max_f32_e32 v217, v218, v217
	s_waitcnt lgkmcnt(6)
	v_mfma_f32_32x32x16_bf16 v[2:17], v[148:151], v[172:175], v[2:17]
	v_sub_f32_e32 v218, v198, v217
	v_mul_f32_e32 v218, 0x3e0293ee, v218
	s_waitcnt lgkmcnt(4)
	v_mfma_f32_32x32x16_bf16 v[2:17], v[152:155], v[202:205], v[2:17]
	v_exp_f32_e32 v218, v218
	s_cmp_eq_u64 vcc, exec
	s_waitcnt lgkmcnt(2)
	v_mfma_f32_32x32x16_bf16 v[2:17], v[156:159], v[206:209], v[2:17]
	s_cselect_b64 s[42:43], -1, 0
	v_cndmask_b32_e64 v219, v218, 1.0, s[42:43]
	s_waitcnt lgkmcnt(0)
	v_mfma_f32_32x32x16_bf16 v[2:17], v[160:163], v[224:227], v[2:17]
	v_mov_b32_e32 v148, v217
	v_mov_b32_e32 v202, v219
	v_cmp_gt_f32_e32 vcc, 1.0, v202
	s_cbranch_vccz .LBB0_95
	s_branch .Lmy_resc1
; __device__ __forceinline__ void mask_tile(f32x16& p0, f32x16& p1, int dq, unsigned W) {
;     const float NEG = -__builtin_inff();
; #pragma unroll
;     for (int r = 0; r < 16; ++r) {
;         const int c = (r & 3) + 8 * (r >> 2);
;         if ((unsigned)(dq - c) >= W) p0[r] = NEG;
;         if ((unsigned)(dq - c - 32) >= W) p1[r] = NEG;
;     }
; }
; template <int VB>
; __device__ __forceinline__ void pv_tile(f32x16* o, int vb0, bf16x8 pa0, bf16x8 pa1, bf16x8 pa2, bf16x8 pa3) {
;     ...
;     PV_D0(0); PV_D0(1); PV_D0(2); PV_D0(3);
.Lmy_pv1_slow:
	s_waitcnt lgkmcnt(6)
	v_mfma_f32_32x32x16_bf16 v[50:65], v[148:151], v[172:175], v[50:65]
	ds_read_b64_tr_b16 v[172:173], v185 offset:0x200
	ds_read_b64_tr_b16 v[174:175], v185 offset:0xa00
	s_waitcnt lgkmcnt(6)
	v_mfma_f32_32x32x16_bf16 v[50:65], v[152:155], v[202:205], v[50:65]
	ds_read_b64_tr_b16 v[202:203], v185 offset:0x1200
	ds_read_b64_tr_b16 v[204:205], v185 offset:0x1a00
	s_waitcnt lgkmcnt(6)
	v_mfma_f32_32x32x16_bf16 v[50:65], v[156:159], v[206:209], v[50:65]
	ds_read_b64_tr_b16 v[206:207], v185 offset:0x2200
	ds_read_b64_tr_b16 v[208:209], v185 offset:0x2a00
	s_waitcnt lgkmcnt(6)
	v_mfma_f32_32x32x16_bf16 v[50:65], v[160:163], v[224:227], v[50:65]
	ds_read_b64_tr_b16 v[224:225], v185 offset:0x3200
	ds_read_b64_tr_b16 v[226:227], v185 offset:0x3a00
	s_waitcnt lgkmcnt(6)
	v_mfma_f32_32x32x16_bf16 v[34:49], v[148:151], v[172:175], v[34:49]
	ds_read_b64_tr_b16 v[172:173], v185 offset:0x400
	ds_read_b64_tr_b16 v[174:175], v185 offset:0xc00
	s_waitcnt lgkmcnt(6)
	v_mfma_f32_32x32x16_bf16 v[34:49], v[152:155], v[202:205], v[34:49]
	ds_read_b64_tr_b16 v[202:203], v185 offset:0x1400
	ds_read_b64_tr_b16 v[204:205], v185 offset:0x1c00
	s_waitcnt lgkmcnt(6)
	v_mfma_f32_32x32x16_bf16 v[34:49], v[156:159], v[206:209], v[34:49]
	ds_read_b64_tr_b16 v[206:207], v185 offset:0x2400
	ds_read_b64_tr_b16 v[208:209], v185 offset:0x2c00
	s_waitcnt lgkmcnt(6)
	v_mfma_f32_32x32x16_bf16 v[34:49], v[160:163], v[224:227], v[34:49]
	ds_read_b64_tr_b16 v[224:225], v185 offset:0x3400
	ds_read_b64_tr_b16 v[226:227], v185 offset:0x3c00
	s_waitcnt lgkmcnt(6)
	v_mfma_f32_32x32x16_bf16 v[18:33], v[148:151], v[172:175], v[18:33]
	ds_read_b64_tr_b16 v[172:173], v185 offset:0x600
	ds_read_b64_tr_b16 v[174:175], v185 offset:0xe00
	s_waitcnt lgkmcnt(6)
	v_mfma_f32_32x32x16_bf16 v[18:33], v[152:155], v[202:205], v[18:33]
	ds_read_b64_tr_b16 v[202:203], v185 offset:0x1600
	ds_read_b64_tr_b16 v[204:205], v185 offset:0x1e00
	s_waitcnt lgkmcnt(6)
	v_mfma_f32_32x32x16_bf16 v[18:33], v[156:159], v[206:209], v[18:33]
	ds_read_b64_tr_b16 v[206:207], v185 offset:0x2600
	ds_read_b64_tr_b16 v[208:209], v185 offset:0x2e00
	s_waitcnt lgkmcnt(6)
	v_mfma_f32_32x32x16_bf16 v[18:33], v[160:163], v[224:227], v[18:33]
	ds_read_b64_tr_b16 v[224:225], v185 offset:0x3600
	ds_read_b64_tr_b16 v[226:227], v185 offset:0x3e00
	s_waitcnt lgkmcnt(6)
	v_mfma_f32_32x32x16_bf16 v[2:17], v[148:151], v[172:175], v[2:17]
	s_cmp_le_i32 s7, s6
	s_waitcnt lgkmcnt(4)
	v_mfma_f32_32x32x16_bf16 v[2:17], v[152:155], v[202:205], v[2:17]
	s_waitcnt lgkmcnt(2)
	v_mfma_f32_32x32x16_bf16 v[2:17], v[156:159], v[206:209], v[2:17]
	s_waitcnt lgkmcnt(0)
	v_mfma_f32_32x32x16_bf16 v[2:17], v[160:163], v[224:227], v[2:17]
	s_cbranch_scc1 .LBB0_91
	v_add_u32_e32 v148, 0x4000007b, v197
	v_cmp_gt_u32_e32 vcc, 2.0, v148
	v_add_u32_e32 v148, 0x5b, v197
	s_nop 0
	v_cndmask_b32_e32 v82, v220, v82, vcc
	v_cmp_lt_u32_e32 vcc, s33, v148
	v_add_u32_e32 v148, 0x7a, v197
	s_nop 0
	v_cndmask_b32_e32 v66, v220, v66, vcc
	v_cmp_lt_u32_e32 vcc, s33, v148
	v_add_u32_e32 v148, 0x5a, v197
	s_nop 0
	v_cndmask_b32_e32 v83, v220, v83, vcc
	v_cmp_lt_u32_e32 vcc, s33, v148
	v_add_u32_e32 v148, 0x79, v197
	s_nop 0
	v_cndmask_b32_e32 v67, v220, v67, vcc
	v_cmp_lt_u32_e32 vcc, s33, v148
	v_add_u32_e32 v148, 0x59, v197
	s_nop 0
	v_cndmask_b32_e32 v84, v220, v84, vcc
	v_cmp_lt_u32_e32 vcc, s33, v148
	v_add_u32_e32 v148, 0x78, v197
	s_nop 0
	v_cndmask_b32_e32 v68, v220, v68, vcc
	v_cmp_lt_u32_e32 vcc, s33, v148
	v_add_u32_e32 v148, 0x58, v197
	s_nop 0
	v_cndmask_b32_e32 v85, v220, v85, vcc
	v_cmp_lt_u32_e32 vcc, s33, v148
	v_add_u32_e32 v148, 0x73, v197
	s_nop 0
	v_cndmask_b32_e32 v69, v220, v69, vcc
	v_cmp_lt_u32_e32 vcc, s33, v148
	v_add_u32_e32 v148, 0x53, v197
	s_nop 0
	v_cndmask_b32_e32 v86, v220, v86, vcc
	v_cmp_lt_u32_e32 vcc, s33, v148
	v_add_u32_e32 v148, 0x72, v197
	s_nop 0
	v_cndmask_b32_e32 v70, v220, v70, vcc
	v_cmp_lt_u32_e32 vcc, s33, v148
	v_add_u32_e32 v148, 0x52, v197
	s_nop 0
	v_cndmask_b32_e32 v87, v220, v87, vcc
	v_cmp_lt_u32_e32 vcc, s33, v148
	v_add_u32_e32 v148, 0x71, v197
	s_nop 0
	v_cndmask_b32_e32 v71, v220, v71, vcc
	v_cmp_lt_u32_e32 vcc, s33, v148
	v_add_u32_e32 v148, 0x51, v197
	s_nop 0
	v_cndmask_b32_e32 v88, v220, v88, vcc
	v_cmp_lt_u32_e32 vcc, s33, v148
	v_add_u32_e32 v148, 0x70, v197
	s_nop 0
	v_cndmask_b32_e32 v72, v220, v72, vcc
	v_cmp_lt_u32_e32 vcc, s33, v148
	v_add_u32_e32 v148, 0x50, v197
	s_nop 0
	v_cndmask_b32_e32 v89, v220, v89, vcc
	v_cmp_lt_u32_e32 vcc, s33, v148
	v_add_u32_e32 v148, 0x6b, v197
	s_nop 0
	v_cndmask_b32_e32 v73, v220, v73, vcc
	v_cmp_lt_u32_e32 vcc, s33, v148
	v_add_u32_e32 v148, 0x4b, v197
	s_nop 0
	v_cndmask_b32_e32 v90, v220, v90, vcc
	v_cmp_lt_u32_e32 vcc, s33, v148
	v_add_u32_e32 v148, 0x6a, v197
	s_nop 0
	v_cndmask_b32_e32 v74, v220, v74, vcc
	v_cmp_lt_u32_e32 vcc, s33, v148
	v_add_u32_e32 v148, 0x4a, v197
	s_nop 0
	v_cndmask_b32_e32 v91, v220, v91, vcc
	v_cmp_lt_u32_e32 vcc, s33, v148
	v_add_u32_e32 v148, 0x69, v197
	s_nop 0
	v_cndmask_b32_e32 v75, v220, v75, vcc
	v_cmp_lt_u32_e32 vcc, s33, v148
	v_add_u32_e32 v148, 0x49, v197
	s_nop 0
	v_cndmask_b32_e32 v92, v220, v92, vcc
	v_cmp_lt_u32_e32 vcc, s33, v148
	v_add_u32_e32 v148, 0x68, v197
	s_nop 0
	v_cndmask_b32_e32 v76, v220, v76, vcc
	v_cmp_lt_u32_e32 vcc, s33, v148
	v_add_u32_e32 v148, 0x48, v197
	s_nop 0
	v_cndmask_b32_e32 v93, v220, v93, vcc
	v_cmp_lt_u32_e32 vcc, s33, v148
	v_add_u32_e32 v148, 0x63, v197
	s_nop 0
	v_cndmask_b32_e32 v77, v220, v77, vcc
	v_cmp_lt_u32_e32 vcc, s33, v148
	v_add_u32_e32 v148, 0x43, v197
	s_nop 0
	v_cndmask_b32_e32 v94, v220, v94, vcc
	v_cmp_lt_u32_e32 vcc, s33, v148
	v_add_u32_e32 v148, 0x62, v197
	s_nop 0
	v_cndmask_b32_e32 v78, v220, v78, vcc
	v_cmp_lt_u32_e32 vcc, s33, v148
	v_add_u32_e32 v148, 0x42, v197
	s_nop 0
	v_cndmask_b32_e32 v95, v220, v95, vcc
	v_cmp_lt_u32_e32 vcc, s33, v148
	v_add_u32_e32 v148, 0x61, v197
	s_nop 0
	v_cndmask_b32_e32 v79, v220, v79, vcc
	v_cmp_lt_u32_e32 vcc, s33, v148
	v_add_u32_e32 v148, 0x41, v197
	s_nop 0
	v_cndmask_b32_e32 v96, v220, v96, vcc
	v_cmp_lt_u32_e32 vcc, s33, v148
	v_add_u32_e32 v148, 0x60, v197
	s_nop 0
	v_cndmask_b32_e32 v80, v220, v80, vcc
	v_cmp_lt_u32_e32 vcc, s33, v148
	v_add_u32_e32 v148, 64, v197
	s_nop 0
	v_cndmask_b32_e32 v97, v220, v97, vcc
	v_cmp_lt_u32_e32 vcc, s33, v148
	s_nop 1
	v_cndmask_b32_e32 v81, v220, v81, vcc

.Lmy_resc1:
	s_and_saveexec_b64 s[0:1], s[38:39]
	ds_write_b32 v187, v202 offset:128
	s_or_b64 exec, exec, s[0:1]
	s_waitcnt lgkmcnt(0)
	ds_read_b128 v[150:153], v186 offset:224
	ds_read_b128 v[154:157], v186 offset:192
	ds_read_b128 v[158:161], v186 offset:160
	ds_read_b128 v[172:175], v186 offset:128
	s_waitcnt lgkmcnt(3)
	v_pk_mul_f32 v[64:65], v[64:65], v[152:153]
	s_waitcnt lgkmcnt(2)
	v_pk_mul_f32 v[60:61], v[60:61], v[156:157]
	s_waitcnt lgkmcnt(1)
	v_pk_mul_f32 v[56:57], v[56:57], v[160:161]
	s_waitcnt lgkmcnt(0)
	v_pk_mul_f32 v[52:53], v[52:53], v[174:175]
	v_pk_mul_f32 v[62:63], v[62:63], v[150:151]
	v_pk_mul_f32 v[58:59], v[58:59], v[154:155]
	v_pk_mul_f32 v[54:55], v[54:55], v[158:159]
	v_pk_mul_f32 v[50:51], v[50:51], v[172:173]
	v_pk_mul_f32 v[48:49], v[48:49], v[152:153]
	v_pk_mul_f32 v[44:45], v[44:45], v[156:157]
	v_pk_mul_f32 v[40:41], v[40:41], v[160:161]
	v_pk_mul_f32 v[36:37], v[36:37], v[174:175]
	v_pk_mul_f32 v[46:47], v[46:47], v[150:151]
	v_pk_mul_f32 v[42:43], v[42:43], v[154:155]
	v_pk_mul_f32 v[38:39], v[38:39], v[158:159]
	v_pk_mul_f32 v[34:35], v[34:35], v[172:173]
	v_pk_mul_f32 v[32:33], v[32:33], v[152:153]
	v_pk_mul_f32 v[28:29], v[28:29], v[156:157]
	v_pk_mul_f32 v[24:25], v[24:25], v[160:161]
	v_pk_mul_f32 v[20:21], v[20:21], v[174:175]
	v_pk_mul_f32 v[30:31], v[30:31], v[150:151]
	v_pk_mul_f32 v[26:27], v[26:27], v[154:155]
	v_pk_mul_f32 v[22:23], v[22:23], v[158:159]
	v_pk_mul_f32 v[18:19], v[18:19], v[172:173]
	v_pk_mul_f32 v[16:17], v[16:17], v[152:153]
	v_pk_mul_f32 v[12:13], v[12:13], v[156:157]
	v_pk_mul_f32 v[8:9], v[8:9], v[160:161]
	v_pk_mul_f32 v[4:5], v[4:5], v[174:175]
	v_pk_mul_f32 v[14:15], v[14:15], v[150:151]
	v_pk_mul_f32 v[10:11], v[10:11], v[154:155]
	v_pk_mul_f32 v[6:7], v[6:7], v[158:159]
	v_pk_mul_f32 v[2:3], v[2:3], v[172:173]
